# baseline (speedup 1.0000x reference)
; #define RAW_BARRIER() do { asm volatile("s_waitcnt lgkmcnt(0)" ::: "memory"); __builtin_amdgcn_s_barrier(); } while (0)
; #define GLDS_TILE(kt, st) do { _Pragma("unroll") for (int _i = 0; _i < NP; ++_i) GLDS_PIECE(_i, kt, st); } while (0)
;     ...
;     constexpr int NH = NI >= 4 ? NI / 2 : NI;
;     constexpr int NP = 2 + NB, IVL = (4 * NI) / NP;
;     RAW_BARRIER();
;     GLDS_TILE(0, 0);
;     GLDS_TILE(1, 1);
;     int st = 0;
;     for (int kt = 0; kt < nk - 1; ++kt) {
;         if (NI == 8) asm volatile("s_waitcnt vmcnt(6)" ::: "memory"); else if (NI == 4) asm volatile("s_waitcnt vmcnt(4)" ::: "memory"); else asm volatile("s_waitcnt vmcnt(3)" ::: "memory");
;         RAW_BARRIER();
;         const int s2 = st >= 1 ? st - 1 : 2;
;         const bool ld = kt + 2 < nk;
;         STEP_TILE(st, ld, kt + 2, s2);
;         st = st == 2 ? 0 : st + 1;
;     }
.LBB0_977:
	s_mul_i32 s6, s1, 0x6000
	s_add_i32 s7, s6, 0
	s_waitcnt vmcnt(6)
	v_add_u32_e32 v148, s7, v134
	v_add_u32_e32 v155, s7, v135
	s_waitcnt lgkmcnt(0)
	s_barrier
	ds_read_b128 v[158:161], v155 offset:8192
	ds_read_b128 v[136:139], v148
	ds_read_b128 v[140:143], v148 offset:1024
	ds_read_b128 v[144:147], v148 offset:2048
	ds_read_b128 v[148:151], v148 offset:3072
	ds_read_b128 v[162:165], v155 offset:9216
	ds_read_b128 v[166:169], v155 offset:10240
	ds_read_b128 v[170:173], v155 offset:11264
	s_addk_i32 s6, 0xa000
	s_cmp_gt_i32 s1, 0
	s_setprio 1
	s_waitcnt lgkmcnt(6)
	v_mfma_f32_16x16x32_bf16 v[126:129], v[158:161], v[136:139], v[126:129]
	s_cselect_b32 s6, s6, 0xc000
	v_add_u32_e32 v214, s6, v32
	v_lshl_add_u64 v[152:153], v[132:133], 0, s[4:5]
	s_waitcnt lgkmcnt(5)
	v_mfma_f32_16x16x32_bf16 v[110:113], v[158:161], v[140:143], v[110:113]
	v_lshl_add_u64 v[212:213], v[130:131], 0, s[4:5]
	v_lshl_add_u64 v[182:183], v[152:153], 0, s[10:11]
	v_add_u32_e32 v215, 0x2000, v214
	s_waitcnt lgkmcnt(4)
	v_mfma_f32_16x16x32_bf16 v[82:85], v[158:161], v[144:147], v[82:85]
	s_waitcnt lgkmcnt(3)
	v_mfma_f32_16x16x32_bf16 v[50:53], v[158:161], v[148:151], v[50:53]
	v_lshl_add_u64 v[158:159], v[212:213], 0, s[12:13]
	s_waitcnt lgkmcnt(2)
	v_mfma_f32_16x16x32_bf16 v[122:125], v[162:165], v[136:139], v[122:125]
	v_readfirstlane_b32 s6, v214
	s_mov_b32 m0, s6
	s_nop 0
	global_load_lds_dwordx4 v[158:159], off
	ds_read_b128 v[158:161], v155 offset:12288
	ds_read_b128 v[174:177], v155 offset:13312
	ds_read_b128 v[178:181], v155 offset:14336
	ds_read_b128 v[208:211], v155 offset:15360
	v_mfma_f32_16x16x32_bf16 v[102:105], v[162:165], v[140:143], v[102:105]
	v_mfma_f32_16x16x32_bf16 v[70:73], v[162:165], v[144:147], v[70:73]
	v_mfma_f32_16x16x32_bf16 v[38:41], v[162:165], v[148:151], v[38:41]
	s_waitcnt lgkmcnt(5)
	v_mfma_f32_16x16x32_bf16 v[118:121], v[166:169], v[136:139], v[118:121]
	v_mfma_f32_16x16x32_bf16 v[94:97], v[166:169], v[140:143], v[94:97]
	v_add_u32_e32 v155, 0x1000, v214
	v_lshl_add_u64 v[162:163], v[212:213], 0, s[14:15]
	v_readfirstlane_b32 s6, v155
	s_mov_b32 m0, s6
	s_nop 0
	global_load_lds_dwordx4 v[162:163], off
	v_mfma_f32_16x16x32_bf16 v[62:65], v[166:169], v[144:147], v[62:65]
	v_mfma_f32_16x16x32_bf16 v[28:31], v[166:169], v[148:151], v[28:31]
	s_waitcnt lgkmcnt(4)
	v_mfma_f32_16x16x32_bf16 v[114:117], v[170:173], v[136:139], v[114:117]
	v_mfma_f32_16x16x32_bf16 v[86:89], v[170:173], v[140:143], v[86:89]
	v_mfma_f32_16x16x32_bf16 v[54:57], v[170:173], v[144:147], v[54:57]
	v_readfirstlane_b32 s6, v215
	s_mov_b32 m0, s6
	s_nop 0
	global_load_lds_dwordx4 v[182:183], off
	v_mfma_f32_16x16x32_bf16 v[20:23], v[170:173], v[148:151], v[20:23]
	s_waitcnt lgkmcnt(0)
	v_mfma_f32_16x16x32_bf16 v[106:109], v[158:161], v[136:139], v[106:109]
	v_mfma_f32_16x16x32_bf16 v[74:77], v[158:161], v[140:143], v[74:77]
	v_mfma_f32_16x16x32_bf16 v[42:45], v[158:161], v[144:147], v[42:45]
	v_mfma_f32_16x16x32_bf16 v[12:15], v[158:161], v[148:151], v[12:15]
	v_add_u32_e32 v155, 0x3000, v214
	v_lshl_add_u64 v[158:159], v[152:153], 0, s[16:17]
	v_readfirstlane_b32 s6, v155
	s_mov_b32 m0, s6
	s_nop 0
	global_load_lds_dwordx4 v[158:159], off
	v_mfma_f32_16x16x32_bf16 v[98:101], v[174:177], v[136:139], v[98:101]
	v_mfma_f32_16x16x32_bf16 v[66:69], v[174:177], v[140:143], v[66:69]
	v_mfma_f32_16x16x32_bf16 v[34:37], v[174:177], v[144:147], v[34:37]
	v_mfma_f32_16x16x32_bf16 v[8:11], v[174:177], v[148:151], v[8:11]
	v_mfma_f32_16x16x32_bf16 v[90:93], v[178:181], v[136:139], v[90:93]
	v_add_u32_e32 v155, 0x4000, v214
	v_lshl_add_u64 v[158:159], v[152:153], 0, s[76:77]
	v_readfirstlane_b32 s6, v155
	s_mov_b32 m0, s6
	s_nop 0
	global_load_lds_dwordx4 v[158:159], off
	v_mfma_f32_16x16x32_bf16 v[58:61], v[178:181], v[140:143], v[58:61]
	v_mfma_f32_16x16x32_bf16 v[24:27], v[178:181], v[144:147], v[24:27]
	v_mfma_f32_16x16x32_bf16 v[4:7], v[178:181], v[148:151], v[4:7]
	v_mfma_f32_16x16x32_bf16 v[78:81], v[208:211], v[136:139], v[78:81]
	v_mfma_f32_16x16x32_bf16 v[46:49], v[208:211], v[140:143], v[46:49]
	v_add_u32_e32 v138, 0x5000, v214
	v_lshl_add_u64 v[136:137], v[152:153], 0, s[84:85]
	v_readfirstlane_b32 s6, v138
	s_mov_b32 m0, s6
	s_nop 0
	global_load_lds_dwordx4 v[136:137], off
	v_mfma_f32_16x16x32_bf16 v[16:19], v[208:211], v[144:147], v[16:19]
	v_mfma_f32_16x16x32_bf16 v[0:3], v[208:211], v[148:151], v[0:3]
	s_nop 0
	s_add_i32 s6, s1, 1
	s_cmp_lg_u32 s1, 2
	s_cselect_b32 s1, s6, 0
	s_add_u32 s4, s4, 0x80
	s_addc_u32 s5, s5, 0
	s_cmpk_lg_i32 s4, 0xf00
	s_cbranch_scc1 .LBB0_977
	s_waitcnt vmcnt(6)
	v_add_u32_e32 v32, 0, v134
	v_add_u32_e32 v152, 0, v135
	s_waitcnt lgkmcnt(0)
	s_barrier
; #define RAW_BARRIER() do { asm volatile("s_waitcnt lgkmcnt(0)" ::: "memory"); __builtin_amdgcn_s_barrier(); } while (0)
;     ...
;     asm volatile("s_waitcnt vmcnt(0)" ::: "memory");
;     RAW_BARRIER();
;     STEP_TILE(st, false, 0, 0);
;     RAW_BARRIER();
	ds_read_b128 v[130:133], v32
	ds_read_b128 v[136:139], v32 offset:1024
	ds_read_b128 v[140:143], v32 offset:2048
	ds_read_b128 v[144:147], v32 offset:3072
	ds_read_b128 v[148:151], v152 offset:8192
	ds_read_b128 v[158:161], v152 offset:9216
	ds_read_b128 v[162:165], v152 offset:10240
	ds_read_b128 v[166:169], v152 offset:11264
	s_sext_i32_i16 s0, s0
	s_setprio 1
	s_waitcnt lgkmcnt(0)
	v_mfma_f32_16x16x32_bf16 v[126:129], v[148:151], v[130:133], v[126:129]
	v_mfma_f32_16x16x32_bf16 v[110:113], v[148:151], v[136:139], v[110:113]
	v_mfma_f32_16x16x32_bf16 v[82:85], v[148:151], v[140:143], v[82:85]
	v_mfma_f32_16x16x32_bf16 v[50:53], v[148:151], v[144:147], v[50:53]
	v_mfma_f32_16x16x32_bf16 v[122:125], v[158:161], v[130:133], v[122:125]
	ds_read_b128 v[148:151], v152 offset:12288
	ds_read_b128 v[170:173], v152 offset:13312
	ds_read_b128 v[174:177], v152 offset:14336
	ds_read_b128 v[178:181], v152 offset:15360
	v_mfma_f32_16x16x32_bf16 v[102:105], v[158:161], v[136:139], v[102:105]
	v_mfma_f32_16x16x32_bf16 v[70:73], v[158:161], v[140:143], v[70:73]
	v_mfma_f32_16x16x32_bf16 v[38:41], v[158:161], v[144:147], v[38:41]
	v_mfma_f32_16x16x32_bf16 v[94:97], v[162:165], v[136:139], v[94:97]
	v_mfma_f32_16x16x32_bf16 v[158:161], v[162:165], v[130:133], v[118:121]
	v_mfma_f32_16x16x32_bf16 v[62:65], v[162:165], v[140:143], v[62:65]
	v_mfma_f32_16x16x32_bf16 v[28:31], v[162:165], v[144:147], v[28:31]
	v_mfma_f32_16x16x32_bf16 v[208:211], v[166:169], v[136:139], v[86:89]
	v_mfma_f32_16x16x32_bf16 v[54:57], v[166:169], v[140:143], v[54:57]
	v_mfma_f32_16x16x32_bf16 v[162:165], v[166:169], v[130:133], v[114:117]
	v_mfma_f32_16x16x32_bf16 v[20:23], v[166:169], v[144:147], v[20:23]
	s_waitcnt lgkmcnt(0)
	v_mfma_f32_16x16x32_bf16 v[42:45], v[148:151], v[140:143], v[42:45]
	v_mfma_f32_16x16x32_bf16 v[12:15], v[148:151], v[144:147], v[12:15]
	v_mfma_f32_16x16x32_bf16 v[166:169], v[148:151], v[130:133], v[106:109]
	v_mfma_f32_16x16x32_bf16 v[212:215], v[148:151], v[136:139], v[74:77]
	v_mfma_f32_16x16x32_bf16 v[148:151], v[170:173], v[130:133], v[98:101]
	v_mfma_f32_16x16x32_bf16 v[8:11], v[170:173], v[144:147], v[8:11]
	v_mfma_f32_16x16x32_bf16 v[216:219], v[170:173], v[136:139], v[66:69]
	v_mfma_f32_16x16x32_bf16 v[220:223], v[170:173], v[140:143], v[34:37]
	v_mfma_f32_16x16x32_bf16 v[170:173], v[174:177], v[130:133], v[90:93]
	v_mfma_f32_16x16x32_bf16 v[24:27], v[174:177], v[140:143], v[24:27]
	v_mfma_f32_16x16x32_bf16 v[46:49], v[178:181], v[136:139], v[46:49]
	v_mfma_f32_16x16x32_bf16 v[224:227], v[174:177], v[136:139], v[58:61]
	v_mfma_f32_16x16x32_bf16 v[174:177], v[174:177], v[144:147], v[4:7]
	v_mfma_f32_16x16x32_bf16 v[130:133], v[178:181], v[130:133], v[78:81]
	v_mfma_f32_16x16x32_bf16 v[134:137], v[178:181], v[140:143], v[16:19]
	v_mfma_f32_16x16x32_bf16 v[138:141], v[178:181], v[144:147], v[0:3]
	s_setprio 0
	s_waitcnt vmcnt(0)
	s_waitcnt lgkmcnt(0)
	s_barrier
	ds_read_b128 v[142:145], v32 offset:24576
	ds_read_b128 v[178:181], v32 offset:25600
	ds_read_b128 v[228:231], v32 offset:26624
	ds_read_b128 v[232:235], v32 offset:27648
	ds_read_b128 v[0:3], v152 offset:32768
	ds_read_b128 v[4:7], v152 offset:33792
	ds_read_b128 v[16:19], v152 offset:34816
	ds_read_b128 v[34:37], v152 offset:35840
	s_setprio 1
	s_waitcnt lgkmcnt(0)
	v_mfma_f32_16x16x32_bf16 v[118:121], v[0:3], v[142:145], v[126:129]
	v_mfma_f32_16x16x32_bf16 v[98:101], v[0:3], v[178:181], v[110:113]
	v_mfma_f32_16x16x32_bf16 v[82:85], v[0:3], v[228:231], v[82:85]
	v_mfma_f32_16x16x32_bf16 v[66:69], v[0:3], v[232:235], v[50:53]
	v_mfma_f32_16x16x32_bf16 v[114:117], v[4:7], v[142:145], v[122:125]
	ds_read_b128 v[0:3], v152 offset:36864
	ds_read_b128 v[236:239], v152 offset:37888
	ds_read_b128 v[240:243], v152 offset:38912
	ds_read_b128 v[244:247], v152 offset:39936
	v_mfma_f32_16x16x32_bf16 v[106:109], v[4:7], v[178:181], v[102:105]
	v_mfma_f32_16x16x32_bf16 v[86:89], v[4:7], v[228:231], v[70:73]
	v_mfma_f32_16x16x32_bf16 v[70:73], v[4:7], v[232:235], v[38:41]
	v_mfma_f32_16x16x32_bf16 v[122:125], v[16:19], v[142:145], v[158:161]
	v_mfma_f32_16x16x32_bf16 v[102:105], v[16:19], v[178:181], v[94:97]
	v_mfma_f32_16x16x32_bf16 v[90:93], v[16:19], v[228:231], v[62:65]
	v_mfma_f32_16x16x32_bf16 v[74:77], v[16:19], v[232:235], v[28:31]
	v_mfma_f32_16x16x32_bf16 v[126:129], v[34:37], v[142:145], v[162:165]
	v_mfma_f32_16x16x32_bf16 v[110:113], v[34:37], v[178:181], v[208:211]
	v_mfma_f32_16x16x32_bf16 v[94:97], v[34:37], v[228:231], v[54:57]
	v_mfma_f32_16x16x32_bf16 v[78:81], v[34:37], v[232:235], v[20:23]
	s_waitcnt lgkmcnt(0)
	v_mfma_f32_16x16x32_bf16 v[50:53], v[0:3], v[142:145], v[166:169]
	v_mfma_f32_16x16x32_bf16 v[34:37], v[0:3], v[178:181], v[212:215]
	v_mfma_f32_16x16x32_bf16 v[16:19], v[0:3], v[228:231], v[42:45]
	v_mfma_f32_16x16x32_bf16 v[0:3], v[0:3], v[232:235], v[12:15]
	v_mfma_f32_16x16x32_bf16 v[58:61], v[236:239], v[142:145], v[148:151]
	v_mfma_f32_16x16x32_bf16 v[38:41], v[236:239], v[178:181], v[216:219]
	v_mfma_f32_16x16x32_bf16 v[20:23], v[236:239], v[228:231], v[220:223]
	v_mfma_f32_16x16x32_bf16 v[4:7], v[236:239], v[232:235], v[8:11]
	v_mfma_f32_16x16x32_bf16 v[54:57], v[240:243], v[142:145], v[170:173]
	v_mfma_f32_16x16x32_bf16 v[42:45], v[240:243], v[178:181], v[224:227]
	v_mfma_f32_16x16x32_bf16 v[24:27], v[240:243], v[228:231], v[24:27]
	v_mfma_f32_16x16x32_bf16 v[8:11], v[240:243], v[232:235], v[174:177]
	v_mfma_f32_16x16x32_bf16 v[62:65], v[244:247], v[142:145], v[130:133]
	v_mfma_f32_16x16x32_bf16 v[46:49], v[244:247], v[178:181], v[46:49]
	v_mfma_f32_16x16x32_bf16 v[28:31], v[244:247], v[228:231], v[134:137]
	v_mfma_f32_16x16x32_bf16 v[12:15], v[244:247], v[232:235], v[138:141]
	s_setprio 0
	v_mov_b32_e32 v32, v186
	s_waitcnt lgkmcnt(0)
	s_barrier
;     __device__ __forceinline__ bf16_t* H() const { return (bf16_t*)(ws + OFF_H); }
;     __device__ __forceinline__ bf16_t* U() const { return (bf16_t*)(ws + OFF_U); }
;     __device__ __forceinline__ bf16_t* Vs() const { return (bf16_t*)(ws + OFF_Vs); }
; DEV void wst_put4(char* wsm, int row, int col, float a, float b, float c, float d) { uint2 w; w.x = pk_bf16(a, b); w.y = pk_bf16(c, d); *(uint2*)(wsm + row * WST_ROW + col * 2) = w; }
; template <int H>
; DEV void epi1_group(const Params& p, int l, bool samp, int rbase, int g64, int fq, int fr, char* wsm, const f32x4 (&acc)[4][8]) {
;     const int cl = fq * 4;
;     const int sc = H * 64 + cl;
;     if (g64 < 12) {
;         bf16_t* dst = g64 < 6 ? p.U() : p.Vs(); const int c0 = (g64 % 6) * 64 + cl;
;     ...
;     } else if (g64 < 90) {
;         const int c0 = (g64 - 42) * 64 + cl;
;         const float* bg = p.b_gate + l * 3072 + c0;
; #pragma unroll
;         for (int ni = 0; ni < 4; ++ni) {
;             const f32x4 b4 = *(const f32x4*)(bg + ni * 16);
; #pragma unroll
;             for (int mi = 0; mi < 4; ++mi) {
;                 f32x4 v = acc[mi][H * 4 + ni] + b4;
; #pragma unroll
;                 for (int j = 0; j < 4; ++j) v[j] = __builtin_amdgcn_rcpf(1.f + __expf(-v[j]));
;                 wst_put4(wsm, mi * 16 + fr, sc + ni * 16, v[0], v[1], v[2], v[3]);
;             }
;         }
	v_readlane_b32 s4, v252, 27
	v_ashrrev_i32_e32 v130, 6, v32
	v_and_b32_e32 v208, 15, v32
	v_bfe_u32 v155, v32, 4, 2
	v_ashrrev_i32_e32 v32, 1, v32
	v_and_b32_e32 v32, 0xffffffc0, v32
	v_lshl_add_u32 v150, s0, 7, v32
	s_lshl_b32 s0, s4, 2
	v_lshlrev_b32_e32 v32, 1, v130
	v_and_or_b32 v210, v32, 2, s0
	s_movk_i32 s0, 0x4400
	v_mul_lo_u32 v32, v130, s0
	s_add_i32 s0, s8, 0xfa00
	s_and_b32 s0, s0, 0xffff
	s_cmp_gt_u32 s0, 11
	v_readlane_b32 s5, v252, 28
	s_cselect_b64 s[6:7], -1, 0
	s_cmp_gt_u32 s4, 2
	s_cselect_b64 s[4:5], -1, 0
	v_or_b32_e32 v152, v150, v208
	v_add_u32_e32 v209, 0, v32
	v_lshlrev_b32_e32 v151, 2, v155
	s_mov_b64 s[0:1], -1
	s_and_b64 vcc, exec, s[4:5]
	s_cbranch_vccz .LBB0_1628
	v_readlane_b32 s0, v252, 27
	v_readlane_b32 s1, v252, 28
	s_cmp_gt_u32 s0, 5
	s_mov_b64 s[0:1], -1
	s_cbranch_scc0 .LBB0_1188
	v_cmp_lt_u32_e32 vcc, 29, v210
	s_and_saveexec_b64 s[0:1], vcc
	s_xor_b64 s[8:9], exec, s[0:1]
	s_cbranch_execz .LBB0_1122
	v_cmp_lt_u32_e32 vcc, 33, v210
	s_and_saveexec_b64 s[0:1], vcc
	s_xor_b64 s[10:11], exec, s[0:1]
	s_cbranch_execz .LBB0_1119
	v_cmp_lt_u32_e32 vcc, 37, v210
	s_and_saveexec_b64 s[0:1], vcc
	s_xor_b64 s[0:1], exec, s[0:1]
	s_cbranch_execz .LBB0_1053
	v_cmp_lt_u32_e32 vcc, 41, v210
	s_and_saveexec_b64 s[12:13], vcc
	s_xor_b64 s[12:13], exec, s[12:13]
	s_cbranch_execz .LBB0_987
	s_movk_i32 s14, 0x5a
	v_cmp_gt_u32_e32 vcc, s14, v210
	s_and_saveexec_b64 s[14:15], vcc
	s_cbranch_execz .LBB0_986
	v_lshl_or_b32 v32, v210, 6, v151
	v_readlane_b32 s2, v250, 42
	v_add_u32_e32 v32, 0xfffff580, v32
	v_readlane_b32 s3, v250, 43
	s_nop 1
	v_lshl_add_u64 v[134:135], v[32:33], 2, s[2:3]
	flat_load_dwordx4 v[130:133], v[134:135]
	v_lshlrev_b32_e32 v32, 3, v155
	s_waitcnt vmcnt(0) lgkmcnt(0)
	v_pk_add_f32 v[136:137], v[120:121], v[132:133]
	s_nop 0
	v_mul_f32_e32 v136, 0xbfb8aa3b, v136
	v_exp_f32_e32 v136, v136
	v_pk_add_f32 v[138:139], v[118:119], v[130:131]
	v_add_f32_e32 v136, 1.0, v136
	v_mul_f32_e32 v138, 0xbfb8aa3b, v138
	v_mul_f32_e32 v139, 0xbfb8aa3b, v139
	v_exp_f32_e32 v138, v138
	v_exp_f32_e32 v139, v139
	v_rcp_f32_e32 v140, v136
	v_mul_f32_e32 v136, 0xbfb8aa3b, v137
	v_exp_f32_e32 v136, v136
	v_add_f32_e32 v138, 1.0, v138
	v_add_f32_e32 v139, 1.0, v139
	v_rcp_f32_e32 v138, v138
	v_rcp_f32_e32 v139, v139
	v_add_f32_e32 v136, 1.0, v136
	v_rcp_f32_e32 v137, v136
	v_cvt_pk_bf16_f32 v136, v138, v139
	v_mul_u32_u24_e32 v138, 0x110, v208
	v_cvt_pk_bf16_f32 v137, v140, v137
	v_add3_u32 v32, v209, v32, v138
	ds_write_b64 v32, v[136:137]
	v_pk_add_f32 v[136:137], v[100:101], v[132:133]
	v_pk_add_f32 v[138:139], v[98:99], v[130:131]
	v_mul_f32_e32 v136, 0xbfb8aa3b, v136
	v_exp_f32_e32 v136, v136
	v_mul_f32_e32 v138, 0xbfb8aa3b, v138
	v_mul_f32_e32 v139, 0xbfb8aa3b, v139
	v_exp_f32_e32 v138, v138
	v_add_f32_e32 v136, 1.0, v136
	v_rcp_f32_e32 v140, v136
	v_mul_f32_e32 v136, 0xbfb8aa3b, v137
	v_exp_f32_e32 v139, v139
	v_exp_f32_e32 v136, v136
	v_add_f32_e32 v138, 1.0, v138
	v_rcp_f32_e32 v138, v138
	v_add_f32_e32 v139, 1.0, v139
	v_add_f32_e32 v136, 1.0, v136
	v_rcp_f32_e32 v139, v139
	v_rcp_f32_e32 v137, v136
	v_cvt_pk_bf16_f32 v136, v138, v139
	v_cvt_pk_bf16_f32 v137, v140, v137
	ds_write_b64 v32, v[136:137] offset:4352
	v_pk_add_f32 v[136:137], v[84:85], v[132:133]
	v_pk_add_f32 v[138:139], v[82:83], v[130:131]
	v_mul_f32_e32 v136, 0xbfb8aa3b, v136
	v_exp_f32_e32 v136, v136
	v_pk_add_f32 v[132:133], v[68:69], v[132:133]
	v_pk_add_f32 v[130:131], v[66:67], v[130:131]
	v_mul_f32_e32 v138, 0xbfb8aa3b, v138
	v_add_f32_e32 v136, 1.0, v136
	v_mul_f32_e32 v139, 0xbfb8aa3b, v139
	v_rcp_f32_e32 v140, v136
	v_mul_f32_e32 v136, 0xbfb8aa3b, v137
	v_mul_f32_e32 v130, 0xbfb8aa3b, v130
	v_mul_f32_e32 v131, 0xbfb8aa3b, v131
	v_mul_f32_e32 v132, 0xbfb8aa3b, v132
	v_mul_f32_e32 v133, 0xbfb8aa3b, v133
	v_exp_f32_e32 v138, v138
	v_exp_f32_e32 v139, v139
	v_exp_f32_e32 v136, v136
	v_exp_f32_e32 v130, v130
	v_exp_f32_e32 v131, v131
	v_exp_f32_e32 v132, v132
	v_exp_f32_e32 v133, v133
	v_add_f32_e32 v138, 1.0, v138
	v_add_f32_e32 v139, 1.0, v139
	v_add_f32_e32 v136, 1.0, v136
	v_add_f32_e32 v130, 1.0, v130
	v_add_f32_e32 v131, 1.0, v131
	v_add_f32_e32 v132, 1.0, v132
	v_add_f32_e32 v133, 1.0, v133
	v_rcp_f32_e32 v138, v138
	v_rcp_f32_e32 v139, v139
	v_rcp_f32_e32 v137, v136
	v_rcp_f32_e32 v130, v130
	v_rcp_f32_e32 v131, v131
	v_rcp_f32_e32 v132, v132
	v_rcp_f32_e32 v133, v133
	v_cvt_pk_bf16_f32 v136, v138, v139
	v_cvt_pk_bf16_f32 v137, v140, v137
	v_cvt_pk_bf16_f32 v130, v130, v131
	v_cvt_pk_bf16_f32 v131, v132, v133
	ds_write_b64 v32, v[136:137] offset:8704
	ds_write_b64 v32, v[130:131] offset:13056
	flat_load_dwordx4 v[130:133], v[134:135] offset:64
	s_waitcnt vmcnt(0) lgkmcnt(0)
;     __device__ __forceinline__ bf16_t* H() const { return (bf16_t*)(ws + OFF_H); }
; DEV void wst_put4(char* wsm, int row, int col, float a, float b, float c, float d) { uint2 w; w.x = pk_bf16(a, b); w.y = pk_bf16(c, d); *(uint2*)(wsm + row * WST_ROW + col * 2) = w; }
; template <int H>
; DEV void epi1_group(const Params& p, int l, bool samp, int rbase, int g64, int fq, int fr, char* wsm, const f32x4 (&acc)[4][8]) {
;     ...
;     } else if (g64 < 90) {
;         const int c0 = (g64 - 42) * 64 + cl;
;         const float* bg = p.b_gate + l * 3072 + c0;
; #pragma unroll
;         for (int ni = 0; ni < 4; ++ni) {
;             const f32x4 b4 = *(const f32x4*)(bg + ni * 16);
; #pragma unroll
;             for (int mi = 0; mi < 4; ++mi) {
;                 f32x4 v = acc[mi][H * 4 + ni] + b4;
; #pragma unroll
;                 for (int j = 0; j < 4; ++j) v[j] = __builtin_amdgcn_rcpf(1.f + __expf(-v[j]));
;                 wst_put4(wsm, mi * 16 + fr, sc + ni * 16, v[0], v[1], v[2], v[3]);
;             }
;         }
	v_pk_add_f32 v[136:137], v[116:117], v[132:133]
	s_nop 0
	v_mul_f32_e32 v136, 0xbfb8aa3b, v136
	v_exp_f32_e32 v136, v136
	v_pk_add_f32 v[138:139], v[114:115], v[130:131]
	v_add_f32_e32 v136, 1.0, v136
	v_mul_f32_e32 v138, 0xbfb8aa3b, v138
	v_mul_f32_e32 v139, 0xbfb8aa3b, v139
	v_rcp_f32_e32 v140, v136
	v_mul_f32_e32 v136, 0xbfb8aa3b, v137
	v_exp_f32_e32 v138, v138
	v_exp_f32_e32 v139, v139
	v_exp_f32_e32 v136, v136
	v_add_f32_e32 v138, 1.0, v138
	v_add_f32_e32 v139, 1.0, v139
	v_add_f32_e32 v136, 1.0, v136
	v_rcp_f32_e32 v138, v138
	v_rcp_f32_e32 v139, v139
	v_rcp_f32_e32 v137, v136
	v_cvt_pk_bf16_f32 v136, v138, v139
	v_cvt_pk_bf16_f32 v137, v140, v137
	ds_write_b64 v32, v[136:137] offset:32
	v_pk_add_f32 v[136:137], v[108:109], v[132:133]
	v_pk_add_f32 v[138:139], v[106:107], v[130:131]
	v_mul_f32_e32 v136, 0xbfb8aa3b, v136
	v_exp_f32_e32 v136, v136
	v_mul_f32_e32 v138, 0xbfb8aa3b, v138
	v_mul_f32_e32 v139, 0xbfb8aa3b, v139
	v_exp_f32_e32 v138, v138
	v_add_f32_e32 v136, 1.0, v136
	v_rcp_f32_e32 v140, v136
	v_mul_f32_e32 v136, 0xbfb8aa3b, v137
	v_exp_f32_e32 v139, v139
	v_exp_f32_e32 v136, v136
	v_add_f32_e32 v138, 1.0, v138
	v_rcp_f32_e32 v138, v138
	v_add_f32_e32 v139, 1.0, v139
	v_add_f32_e32 v136, 1.0, v136
	v_rcp_f32_e32 v139, v139
	v_rcp_f32_e32 v137, v136
	v_cvt_pk_bf16_f32 v136, v138, v139
	v_cvt_pk_bf16_f32 v137, v140, v137
	ds_write_b64 v32, v[136:137] offset:4384
	v_pk_add_f32 v[136:137], v[88:89], v[132:133]
	v_pk_add_f32 v[138:139], v[86:87], v[130:131]
	v_mul_f32_e32 v136, 0xbfb8aa3b, v136
	v_exp_f32_e32 v136, v136
	v_pk_add_f32 v[132:133], v[72:73], v[132:133]
	v_pk_add_f32 v[130:131], v[70:71], v[130:131]
	v_mul_f32_e32 v138, 0xbfb8aa3b, v138
	v_add_f32_e32 v136, 1.0, v136
	v_mul_f32_e32 v139, 0xbfb8aa3b, v139
	v_rcp_f32_e32 v140, v136
	v_mul_f32_e32 v136, 0xbfb8aa3b, v137
	v_mul_f32_e32 v130, 0xbfb8aa3b, v130
	v_mul_f32_e32 v131, 0xbfb8aa3b, v131
	v_mul_f32_e32 v132, 0xbfb8aa3b, v132
	v_mul_f32_e32 v133, 0xbfb8aa3b, v133
	v_exp_f32_e32 v138, v138
	v_exp_f32_e32 v139, v139
	v_exp_f32_e32 v136, v136
	v_exp_f32_e32 v130, v130
	v_exp_f32_e32 v131, v131
	v_exp_f32_e32 v132, v132
	v_exp_f32_e32 v133, v133
	v_add_f32_e32 v138, 1.0, v138
	v_add_f32_e32 v139, 1.0, v139
	v_add_f32_e32 v136, 1.0, v136
	v_add_f32_e32 v130, 1.0, v130
	v_add_f32_e32 v131, 1.0, v131
	v_add_f32_e32 v132, 1.0, v132
	v_add_f32_e32 v133, 1.0, v133
	v_rcp_f32_e32 v138, v138
	v_rcp_f32_e32 v139, v139
	v_rcp_f32_e32 v137, v136
	v_rcp_f32_e32 v130, v130
	v_rcp_f32_e32 v131, v131
	v_rcp_f32_e32 v132, v132
	v_rcp_f32_e32 v133, v133
	v_cvt_pk_bf16_f32 v136, v138, v139
	v_cvt_pk_bf16_f32 v137, v140, v137
	v_cvt_pk_bf16_f32 v130, v130, v131
	v_cvt_pk_bf16_f32 v131, v132, v133
	ds_write_b64 v32, v[136:137] offset:8736
	ds_write_b64 v32, v[130:131] offset:13088
	flat_load_dwordx4 v[130:133], v[134:135] offset:128
	s_waitcnt vmcnt(0) lgkmcnt(0)
;     __device__ __forceinline__ bf16_t* H() const { return (bf16_t*)(ws + OFF_H); }
; DEV void wst_put4(char* wsm, int row, int col, float a, float b, float c, float d) { uint2 w; w.x = pk_bf16(a, b); w.y = pk_bf16(c, d); *(uint2*)(wsm + row * WST_ROW + col * 2) = w; }
; template <int H>
; DEV void epi1_group(const Params& p, int l, bool samp, int rbase, int g64, int fq, int fr, char* wsm, const f32x4 (&acc)[4][8]) {
;     ...
;     } else if (g64 < 90) {
;         const int c0 = (g64 - 42) * 64 + cl;
;         const float* bg = p.b_gate + l * 3072 + c0;
; #pragma unroll
;         for (int ni = 0; ni < 4; ++ni) {
;             const f32x4 b4 = *(const f32x4*)(bg + ni * 16);
; #pragma unroll
;             for (int mi = 0; mi < 4; ++mi) {
;                 f32x4 v = acc[mi][H * 4 + ni] + b4;
; #pragma unroll
;                 for (int j = 0; j < 4; ++j) v[j] = __builtin_amdgcn_rcpf(1.f + __expf(-v[j]));
;                 wst_put4(wsm, mi * 16 + fr, sc + ni * 16, v[0], v[1], v[2], v[3]);
;             }
;         }
	v_pk_add_f32 v[136:137], v[124:125], v[132:133]
	s_nop 0
	v_mul_f32_e32 v136, 0xbfb8aa3b, v136
	v_exp_f32_e32 v136, v136
	v_pk_add_f32 v[138:139], v[122:123], v[130:131]
	v_add_f32_e32 v136, 1.0, v136
	v_mul_f32_e32 v138, 0xbfb8aa3b, v138
	v_mul_f32_e32 v139, 0xbfb8aa3b, v139
	v_rcp_f32_e32 v140, v136
	v_mul_f32_e32 v136, 0xbfb8aa3b, v137
	v_exp_f32_e32 v138, v138
	v_exp_f32_e32 v139, v139
	v_exp_f32_e32 v136, v136
	v_add_f32_e32 v138, 1.0, v138
	v_add_f32_e32 v139, 1.0, v139
	v_add_f32_e32 v136, 1.0, v136
	v_rcp_f32_e32 v138, v138
	v_rcp_f32_e32 v139, v139
	v_rcp_f32_e32 v137, v136
	v_cvt_pk_bf16_f32 v136, v138, v139
	v_cvt_pk_bf16_f32 v137, v140, v137
	ds_write_b64 v32, v[136:137] offset:64
	v_pk_add_f32 v[136:137], v[104:105], v[132:133]
	v_pk_add_f32 v[138:139], v[102:103], v[130:131]
	v_mul_f32_e32 v136, 0xbfb8aa3b, v136
	v_exp_f32_e32 v136, v136
	v_mul_f32_e32 v138, 0xbfb8aa3b, v138
	v_mul_f32_e32 v139, 0xbfb8aa3b, v139
	v_exp_f32_e32 v138, v138
	v_add_f32_e32 v136, 1.0, v136
	v_rcp_f32_e32 v140, v136
	v_mul_f32_e32 v136, 0xbfb8aa3b, v137
	v_exp_f32_e32 v139, v139
	v_exp_f32_e32 v136, v136
	v_add_f32_e32 v138, 1.0, v138
	v_rcp_f32_e32 v138, v138
	v_add_f32_e32 v139, 1.0, v139
	v_add_f32_e32 v136, 1.0, v136
	v_rcp_f32_e32 v139, v139
	v_rcp_f32_e32 v137, v136
	v_cvt_pk_bf16_f32 v136, v138, v139
	v_cvt_pk_bf16_f32 v137, v140, v137
	ds_write_b64 v32, v[136:137] offset:4416
	v_pk_add_f32 v[136:137], v[92:93], v[132:133]
	v_pk_add_f32 v[138:139], v[90:91], v[130:131]
	v_mul_f32_e32 v136, 0xbfb8aa3b, v136
	v_exp_f32_e32 v136, v136
	v_pk_add_f32 v[132:133], v[76:77], v[132:133]
	v_pk_add_f32 v[130:131], v[74:75], v[130:131]
	v_mul_f32_e32 v138, 0xbfb8aa3b, v138
	v_add_f32_e32 v136, 1.0, v136
	v_mul_f32_e32 v139, 0xbfb8aa3b, v139
	v_rcp_f32_e32 v140, v136
	v_mul_f32_e32 v136, 0xbfb8aa3b, v137
	v_mul_f32_e32 v130, 0xbfb8aa3b, v130
	v_mul_f32_e32 v131, 0xbfb8aa3b, v131
	v_mul_f32_e32 v132, 0xbfb8aa3b, v132
	v_mul_f32_e32 v133, 0xbfb8aa3b, v133
	v_exp_f32_e32 v138, v138
	v_exp_f32_e32 v139, v139
	v_exp_f32_e32 v136, v136
	v_exp_f32_e32 v130, v130
	v_exp_f32_e32 v131, v131
	v_exp_f32_e32 v132, v132
	v_exp_f32_e32 v133, v133
	v_add_f32_e32 v138, 1.0, v138
	v_add_f32_e32 v139, 1.0, v139
	v_add_f32_e32 v136, 1.0, v136
	v_add_f32_e32 v130, 1.0, v130
	v_add_f32_e32 v131, 1.0, v131
	v_add_f32_e32 v132, 1.0, v132
	v_add_f32_e32 v133, 1.0, v133
	v_rcp_f32_e32 v138, v138
	v_rcp_f32_e32 v139, v139
	v_rcp_f32_e32 v137, v136
	v_rcp_f32_e32 v130, v130
	v_rcp_f32_e32 v131, v131
	v_rcp_f32_e32 v132, v132
	v_rcp_f32_e32 v133, v133
	v_cvt_pk_bf16_f32 v136, v138, v139
	v_cvt_pk_bf16_f32 v137, v140, v137
	v_cvt_pk_bf16_f32 v130, v130, v131
	v_cvt_pk_bf16_f32 v131, v132, v133
	ds_write_b64 v32, v[136:137] offset:8768
	ds_write_b64 v32, v[130:131] offset:13120
	flat_load_dwordx4 v[130:133], v[134:135] offset:192
	s_waitcnt vmcnt(0) lgkmcnt(0)
	v_pk_add_f32 v[134:135], v[128:129], v[132:133]
	s_nop 0
	v_mul_f32_e32 v134, 0xbfb8aa3b, v134
	v_exp_f32_e32 v134, v134
	v_pk_add_f32 v[136:137], v[126:127], v[130:131]
	v_add_f32_e32 v134, 1.0, v134
	v_mul_f32_e32 v136, 0xbfb8aa3b, v136
	v_mul_f32_e32 v137, 0xbfb8aa3b, v137
	v_rcp_f32_e32 v138, v134
	v_mul_f32_e32 v134, 0xbfb8aa3b, v135
	v_exp_f32_e32 v136, v136
	v_exp_f32_e32 v137, v137
	v_exp_f32_e32 v134, v134
	v_add_f32_e32 v136, 1.0, v136
	v_add_f32_e32 v137, 1.0, v137
	v_add_f32_e32 v134, 1.0, v134
	v_rcp_f32_e32 v136, v136
	v_rcp_f32_e32 v137, v137
	v_rcp_f32_e32 v135, v134
	v_cvt_pk_bf16_f32 v134, v136, v137
	v_cvt_pk_bf16_f32 v135, v138, v135
	ds_write_b64 v32, v[134:135] offset:96
	v_pk_add_f32 v[134:135], v[112:113], v[132:133]
	v_pk_add_f32 v[136:137], v[110:111], v[130:131]
	v_mul_f32_e32 v134, 0xbfb8aa3b, v134
	v_exp_f32_e32 v134, v134
	v_mul_f32_e32 v136, 0xbfb8aa3b, v136
	v_mul_f32_e32 v137, 0xbfb8aa3b, v137
	v_exp_f32_e32 v136, v136
	v_add_f32_e32 v134, 1.0, v134
	v_rcp_f32_e32 v138, v134
	v_mul_f32_e32 v134, 0xbfb8aa3b, v135
	v_exp_f32_e32 v137, v137
	v_exp_f32_e32 v134, v134
	v_add_f32_e32 v136, 1.0, v136
	v_rcp_f32_e32 v136, v136
	v_add_f32_e32 v137, 1.0, v137
	v_add_f32_e32 v134, 1.0, v134
	v_rcp_f32_e32 v137, v137
	v_rcp_f32_e32 v135, v134
	v_cvt_pk_bf16_f32 v134, v136, v137
	v_cvt_pk_bf16_f32 v135, v138, v135
	ds_write_b64 v32, v[134:135] offset:4448
	v_pk_add_f32 v[134:135], v[96:97], v[132:133]
	v_pk_add_f32 v[136:137], v[94:95], v[130:131]
	v_mul_f32_e32 v134, 0xbfb8aa3b, v134
	v_exp_f32_e32 v134, v134
	v_pk_add_f32 v[132:133], v[80:81], v[132:133]
	v_pk_add_f32 v[130:131], v[78:79], v[130:131]
	v_mul_f32_e32 v136, 0xbfb8aa3b, v136
	v_add_f32_e32 v134, 1.0, v134
	v_mul_f32_e32 v137, 0xbfb8aa3b, v137
	v_rcp_f32_e32 v138, v134
	v_mul_f32_e32 v134, 0xbfb8aa3b, v135
	v_mul_f32_e32 v130, 0xbfb8aa3b, v130
	v_mul_f32_e32 v131, 0xbfb8aa3b, v131
	v_mul_f32_e32 v132, 0xbfb8aa3b, v132
	v_mul_f32_e32 v133, 0xbfb8aa3b, v133
	v_exp_f32_e32 v136, v136
	v_exp_f32_e32 v137, v137
	v_exp_f32_e32 v134, v134
	v_exp_f32_e32 v130, v130
	v_exp_f32_e32 v131, v131
	v_exp_f32_e32 v132, v132
	v_exp_f32_e32 v133, v133
	v_add_f32_e32 v136, 1.0, v136
	v_add_f32_e32 v137, 1.0, v137
	v_add_f32_e32 v134, 1.0, v134
	v_add_f32_e32 v130, 1.0, v130
	v_add_f32_e32 v131, 1.0, v131
	v_add_f32_e32 v132, 1.0, v132
	v_add_f32_e32 v133, 1.0, v133
	v_rcp_f32_e32 v136, v136
	v_rcp_f32_e32 v137, v137
	v_rcp_f32_e32 v135, v134
	v_rcp_f32_e32 v130, v130
	v_rcp_f32_e32 v131, v131
	v_rcp_f32_e32 v132, v132
	v_rcp_f32_e32 v133, v133
	v_cvt_pk_bf16_f32 v134, v136, v137
	v_cvt_pk_bf16_f32 v135, v138, v135
	v_cvt_pk_bf16_f32 v130, v130, v131
	v_cvt_pk_bf16_f32 v131, v132, v133
	ds_write_b64 v32, v[134:135] offset:8800
	ds_write_b64 v32, v[130:131] offset:13152
